# GDN recurrence step rewritten by hand: fma-chained dot products, packed scalar section without register shuffles, in-place state update (about 20 percent fewer issue slots per step)
# speedup vs baseline: 1.0678x; 1.0031x over previous
; DI void gdn_chain(const P& p, int cid, char* smem) {
;     ...
;       GDN_LOAD2(0, A)
;       for (int t0 = 0; t0 < 64; t0 += 8) {
;         float myo = 0.f;
;         const int m0 = t0 >> 1;
;         GDN_LOAD2(m0 + 1, B) GDN_STEP2(0, A)
.LBB0_965:
	s_or_b64 exec, exec, s[0:1]
	s_waitcnt lgkmcnt(0)
	s_barrier
	ds_read_b128 v[8:11], v72 offset:16384
	ds_read_b128 v[12:15], v72 offset:16400
	ds_read_b128 v[16:19], v72 offset:16640
	ds_read_b128 v[20:23], v72 offset:16656
	ds_read_b128 v[24:27], v72
	ds_read_b128 v[28:31], v72 offset:16
	ds_read_b128 v[32:35], v72 offset:256
	ds_read_b128 v[36:39], v72 offset:272
	ds_read2_b32 v[40:41], v80 offset1:32
	ds_read_b128 v[42:45], v96 offset:49152
	ds_read_b128 v[60:63], v96 offset:49168
	s_mov_b32 s0, -8
	v_mov_b32_e32 v56, v77
	v_mov_b32_e32 v57, v76
	s_mov_b32 s1, s14
	v_mov_b32_e32 v58, v81
.Lgdn_rec:
	v_mov_b32_e32 v59, s1
	s_waitcnt lgkmcnt(0)
	ds_read_b128 v[84:87], v56 offset:16384
	ds_read_b128 v[88:91], v56 offset:16400
	ds_read_b128 v[92:95], v56 offset:16640
	ds_read_b128 v[98:101], v56 offset:16656
	ds_read_b128 v[102:105], v56
	ds_read_b128 v[106:109], v56 offset:16
	ds_read_b128 v[120:123], v56 offset:256
	ds_read_b128 v[124:127], v56 offset:272
	ds_read2_b32 v[128:129], v57 offset1:32
	ds_read_b128 v[64:67], v59
	ds_read_b128 v[224:227], v59 offset:16
	v_pk_mul_f32 v[228:229], v[8:9], v[0:1]
	v_pk_mul_f32 v[230:231], v[16:17], v[0:1]
	v_pk_mul_f32 v[232:233], v[24:25], v[0:1]
	v_pk_mul_f32 v[234:235], v[32:33], v[0:1]
	v_pk_fma_f32 v[228:229], v[10:11], v[2:3], v[228:229]
	v_pk_fma_f32 v[230:231], v[18:19], v[2:3], v[230:231]
	v_pk_fma_f32 v[232:233], v[26:27], v[2:3], v[232:233]
	v_pk_fma_f32 v[234:235], v[34:35], v[2:3], v[234:235]
	v_pk_fma_f32 v[228:229], v[12:13], v[4:5], v[228:229]
	v_pk_fma_f32 v[230:231], v[20:21], v[4:5], v[230:231]
	v_pk_fma_f32 v[232:233], v[28:29], v[4:5], v[232:233]
	v_pk_fma_f32 v[234:235], v[36:37], v[4:5], v[234:235]
	v_pk_fma_f32 v[228:229], v[14:15], v[6:7], v[228:229]
	v_pk_fma_f32 v[230:231], v[22:23], v[6:7], v[230:231]
	v_pk_fma_f32 v[232:233], v[30:31], v[6:7], v[232:233]
	v_pk_fma_f32 v[234:235], v[38:39], v[6:7], v[234:235]
	v_add_f32_e32 v228, v228, v229
	v_add_f32_e32 v230, v230, v231
	v_add_f32_e32 v232, v232, v233
	v_add_f32_e32 v234, v234, v235
	v_add_f32_dpp v228, v228, v228 quad_perm:[1,0,3,2] row_mask:0xf bank_mask:0xf bound_ctrl:1
	v_add_f32_dpp v230, v230, v230 quad_perm:[1,0,3,2] row_mask:0xf bank_mask:0xf bound_ctrl:1
	v_add_f32_dpp v232, v232, v232 quad_perm:[1,0,3,2] row_mask:0xf bank_mask:0xf bound_ctrl:1
	v_add_f32_dpp v234, v234, v234 quad_perm:[1,0,3,2] row_mask:0xf bank_mask:0xf bound_ctrl:1
	v_add_f32_dpp v228, v228, v228 quad_perm:[2,3,0,1] row_mask:0xf bank_mask:0xf bound_ctrl:1
	v_add_f32_dpp v230, v230, v230 quad_perm:[2,3,0,1] row_mask:0xf bank_mask:0xf bound_ctrl:1
	v_add_f32_dpp v232, v232, v232 quad_perm:[2,3,0,1] row_mask:0xf bank_mask:0xf bound_ctrl:1
	v_add_f32_dpp v234, v234, v234 quad_perm:[2,3,0,1] row_mask:0xf bank_mask:0xf bound_ctrl:1
	v_add_f32_dpp v236, v228, v228 row_half_mirror row_mask:0xf bank_mask:0xf bound_ctrl:1
	v_add_f32_dpp v240, v230, v230 row_half_mirror row_mask:0xf bank_mask:0xf bound_ctrl:1
	v_add_f32_dpp v238, v232, v232 row_half_mirror row_mask:0xf bank_mask:0xf bound_ctrl:1
	v_add_f32_dpp v241, v234, v234 row_half_mirror row_mask:0xf bank_mask:0xf bound_ctrl:1
	v_mul_f32_e32 v246, v44, v42
	v_fma_f32 v239, -v42, v236, v40
	v_pk_mul_f32 v[240:241], v[42:43], v[240:241] op_sel_hi:[0,1]
	v_pk_mul_f32 v[242:243], v[42:43], v[238:239]
	v_mul_f32_e32 v247, v44, v243
	v_fma_f32 v240, v60, v243, v240
	v_fma_f32 v241, v62, v243, v241
	v_fma_f32 v244, v61, v243, v242
	v_fma_f32 v240, -v44, v240, v41
	v_pk_mul_f32 v[248:249], v[8:9], v[246:247] op_sel:[0,1]
	v_pk_mul_f32 v[250:251], v[10:11], v[246:247] op_sel:[0,1]
	v_pk_mul_f32 v[240:241], v[44:45], v[240:241] op_sel:[1,0] op_sel_hi:[0,1]
	v_pk_mul_f32 v[252:253], v[12:13], v[246:247] op_sel:[0,1]
	v_pk_mul_f32 v[254:255], v[14:15], v[246:247] op_sel:[0,1]
	v_pk_fma_f32 v[0:1], v[246:247], v[0:1], v[248:249] op_sel_hi:[0,1,1]
	v_pk_fma_f32 v[2:3], v[246:247], v[2:3], v[250:251] op_sel_hi:[0,1,1]
	v_pk_fma_f32 v[4:5], v[246:247], v[4:5], v[252:253] op_sel_hi:[0,1,1]
	v_pk_fma_f32 v[6:7], v[246:247], v[6:7], v[254:255] op_sel_hi:[0,1,1]
	v_fma_f32 v245, v63, v240, v241
	v_pk_fma_f32 v[0:1], v[16:17], v[240:241], v[0:1] op_sel_hi:[1,0,1]
	v_pk_fma_f32 v[2:3], v[18:19], v[240:241], v[2:3] op_sel_hi:[1,0,1]
	v_pk_fma_f32 v[4:5], v[20:21], v[240:241], v[4:5] op_sel_hi:[1,0,1]
	v_pk_fma_f32 v[6:7], v[22:23], v[240:241], v[6:7] op_sel_hi:[1,0,1]
	v_cndmask_b32_e64 v83, 0, v244, s[78:79]
	v_cndmask_b32_e64 v83, v83, v245, s[80:81]
	s_waitcnt lgkmcnt(0)
; DI void gdn_chain(const P& p, int cid, char* smem) {
;     ...
;       GDN_LOAD2(0, A)
;       for (int t0 = 0; t0 < 64; t0 += 8) {
;         float myo = 0.f;
;         const int m0 = t0 >> 1;
;         GDN_LOAD2(m0 + 1, B) GDN_STEP2(0, A)
;         GDN_LOAD2(m0 + 2, A) GDN_STEP2(1, B)
;         GDN_LOAD2(m0 + 3, B) GDN_STEP2(2, A)
	ds_read_b128 v[8:11], v56 offset:16896
	ds_read_b128 v[12:15], v56 offset:16912
	ds_read_b128 v[16:19], v56 offset:17152
	ds_read_b128 v[20:23], v56 offset:17168
	ds_read_b128 v[24:27], v56 offset:512
	ds_read_b128 v[28:31], v56 offset:528
	ds_read_b128 v[32:35], v56 offset:768
	ds_read_b128 v[36:39], v56 offset:784
	ds_read2_b32 v[40:41], v57 offset0:64 offset1:96
	ds_read_b128 v[42:45], v59 offset:32
	ds_read_b128 v[60:63], v59 offset:48
	v_pk_mul_f32 v[228:229], v[84:85], v[0:1]
	v_pk_mul_f32 v[230:231], v[92:93], v[0:1]
	v_pk_mul_f32 v[232:233], v[102:103], v[0:1]
	v_pk_mul_f32 v[234:235], v[120:121], v[0:1]
	v_pk_fma_f32 v[228:229], v[86:87], v[2:3], v[228:229]
	v_pk_fma_f32 v[230:231], v[94:95], v[2:3], v[230:231]
	v_pk_fma_f32 v[232:233], v[104:105], v[2:3], v[232:233]
	v_pk_fma_f32 v[234:235], v[122:123], v[2:3], v[234:235]
	v_pk_fma_f32 v[228:229], v[88:89], v[4:5], v[228:229]
	v_pk_fma_f32 v[230:231], v[98:99], v[4:5], v[230:231]
	v_pk_fma_f32 v[232:233], v[106:107], v[4:5], v[232:233]
	v_pk_fma_f32 v[234:235], v[124:125], v[4:5], v[234:235]
	v_pk_fma_f32 v[228:229], v[90:91], v[6:7], v[228:229]
	v_pk_fma_f32 v[230:231], v[100:101], v[6:7], v[230:231]
	v_pk_fma_f32 v[232:233], v[108:109], v[6:7], v[232:233]
	v_pk_fma_f32 v[234:235], v[126:127], v[6:7], v[234:235]
	v_add_f32_e32 v228, v228, v229
	v_add_f32_e32 v230, v230, v231
	v_add_f32_e32 v232, v232, v233
	v_add_f32_e32 v234, v234, v235
	v_add_f32_dpp v228, v228, v228 quad_perm:[1,0,3,2] row_mask:0xf bank_mask:0xf bound_ctrl:1
	v_add_f32_dpp v230, v230, v230 quad_perm:[1,0,3,2] row_mask:0xf bank_mask:0xf bound_ctrl:1
	v_add_f32_dpp v232, v232, v232 quad_perm:[1,0,3,2] row_mask:0xf bank_mask:0xf bound_ctrl:1
	v_add_f32_dpp v234, v234, v234 quad_perm:[1,0,3,2] row_mask:0xf bank_mask:0xf bound_ctrl:1
	v_add_f32_dpp v228, v228, v228 quad_perm:[2,3,0,1] row_mask:0xf bank_mask:0xf bound_ctrl:1
	v_add_f32_dpp v230, v230, v230 quad_perm:[2,3,0,1] row_mask:0xf bank_mask:0xf bound_ctrl:1
	v_add_f32_dpp v232, v232, v232 quad_perm:[2,3,0,1] row_mask:0xf bank_mask:0xf bound_ctrl:1
	v_add_f32_dpp v234, v234, v234 quad_perm:[2,3,0,1] row_mask:0xf bank_mask:0xf bound_ctrl:1
	v_add_f32_dpp v236, v228, v228 row_half_mirror row_mask:0xf bank_mask:0xf bound_ctrl:1
	v_add_f32_dpp v240, v230, v230 row_half_mirror row_mask:0xf bank_mask:0xf bound_ctrl:1
	v_add_f32_dpp v238, v232, v232 row_half_mirror row_mask:0xf bank_mask:0xf bound_ctrl:1
	v_add_f32_dpp v241, v234, v234 row_half_mirror row_mask:0xf bank_mask:0xf bound_ctrl:1
	v_mul_f32_e32 v246, v66, v64
	v_fma_f32 v239, -v64, v236, v128
	v_pk_mul_f32 v[240:241], v[64:65], v[240:241] op_sel_hi:[0,1]
	v_pk_mul_f32 v[242:243], v[64:65], v[238:239]
	v_mul_f32_e32 v247, v66, v243
	v_fma_f32 v240, v224, v243, v240
	v_fma_f32 v241, v226, v243, v241
	v_fma_f32 v244, v225, v243, v242
	v_fma_f32 v240, -v66, v240, v129
	v_pk_mul_f32 v[248:249], v[84:85], v[246:247] op_sel:[0,1]
	v_pk_mul_f32 v[250:251], v[86:87], v[246:247] op_sel:[0,1]
	v_pk_mul_f32 v[240:241], v[66:67], v[240:241] op_sel:[1,0] op_sel_hi:[0,1]
	v_pk_mul_f32 v[252:253], v[88:89], v[246:247] op_sel:[0,1]
	v_pk_mul_f32 v[254:255], v[90:91], v[246:247] op_sel:[0,1]
	v_pk_fma_f32 v[0:1], v[246:247], v[0:1], v[248:249] op_sel_hi:[0,1,1]
	v_pk_fma_f32 v[2:3], v[246:247], v[2:3], v[250:251] op_sel_hi:[0,1,1]
	v_pk_fma_f32 v[4:5], v[246:247], v[4:5], v[252:253] op_sel_hi:[0,1,1]
	v_pk_fma_f32 v[6:7], v[246:247], v[6:7], v[254:255] op_sel_hi:[0,1,1]
	v_fma_f32 v245, v227, v240, v241
	v_pk_fma_f32 v[0:1], v[92:93], v[240:241], v[0:1] op_sel_hi:[1,0,1]
	v_pk_fma_f32 v[2:3], v[94:95], v[240:241], v[2:3] op_sel_hi:[1,0,1]
	v_pk_fma_f32 v[4:5], v[98:99], v[240:241], v[4:5] op_sel_hi:[1,0,1]
	v_pk_fma_f32 v[6:7], v[100:101], v[240:241], v[6:7] op_sel_hi:[1,0,1]
	v_cndmask_b32_e64 v83, v83, v244, s[82:83]
	v_cndmask_b32_e64 v83, v83, v245, s[84:85]
	s_waitcnt lgkmcnt(0)
	ds_read_b128 v[84:87], v56 offset:17408
	ds_read_b128 v[88:91], v56 offset:17424
	ds_read_b128 v[92:95], v56 offset:17664
	ds_read_b128 v[98:101], v56 offset:17680
	ds_read_b128 v[102:105], v56 offset:1024
	ds_read_b128 v[106:109], v56 offset:1040
	ds_read_b128 v[120:123], v56 offset:1280
	ds_read_b128 v[124:127], v56 offset:1296
	ds_read2_b32 v[128:129], v57 offset0:128 offset1:160
	ds_read_b128 v[64:67], v59 offset:64
	ds_read_b128 v[224:227], v59 offset:80
	v_pk_mul_f32 v[228:229], v[8:9], v[0:1]
	v_pk_mul_f32 v[230:231], v[16:17], v[0:1]
	v_pk_mul_f32 v[232:233], v[24:25], v[0:1]
	v_pk_mul_f32 v[234:235], v[32:33], v[0:1]
	v_pk_fma_f32 v[228:229], v[10:11], v[2:3], v[228:229]
	v_pk_fma_f32 v[230:231], v[18:19], v[2:3], v[230:231]
	v_pk_fma_f32 v[232:233], v[26:27], v[2:3], v[232:233]
	v_pk_fma_f32 v[234:235], v[34:35], v[2:3], v[234:235]
	v_pk_fma_f32 v[228:229], v[12:13], v[4:5], v[228:229]
	v_pk_fma_f32 v[230:231], v[20:21], v[4:5], v[230:231]
	v_pk_fma_f32 v[232:233], v[28:29], v[4:5], v[232:233]
	v_pk_fma_f32 v[234:235], v[36:37], v[4:5], v[234:235]
	v_pk_fma_f32 v[228:229], v[14:15], v[6:7], v[228:229]
	v_pk_fma_f32 v[230:231], v[22:23], v[6:7], v[230:231]
	v_pk_fma_f32 v[232:233], v[30:31], v[6:7], v[232:233]
	v_pk_fma_f32 v[234:235], v[38:39], v[6:7], v[234:235]
	v_add_f32_e32 v228, v228, v229
	v_add_f32_e32 v230, v230, v231
	v_add_f32_e32 v232, v232, v233
	v_add_f32_e32 v234, v234, v235
	v_add_f32_dpp v228, v228, v228 quad_perm:[1,0,3,2] row_mask:0xf bank_mask:0xf bound_ctrl:1
	v_add_f32_dpp v230, v230, v230 quad_perm:[1,0,3,2] row_mask:0xf bank_mask:0xf bound_ctrl:1
	v_add_f32_dpp v232, v232, v232 quad_perm:[1,0,3,2] row_mask:0xf bank_mask:0xf bound_ctrl:1
	v_add_f32_dpp v234, v234, v234 quad_perm:[1,0,3,2] row_mask:0xf bank_mask:0xf bound_ctrl:1
; DI void gdn_chain(const P& p, int cid, char* smem) {
;     ...
;       for (int t0 = 0; t0 < 64; t0 += 8) {
;         float myo = 0.f;
;         const int m0 = t0 >> 1;
;         GDN_LOAD2(m0 + 1, B) GDN_STEP2(0, A)
;         GDN_LOAD2(m0 + 2, A) GDN_STEP2(1, B)
;         GDN_LOAD2(m0 + 3, B) GDN_STEP2(2, A)
;         GDN_LOAD2(m0 + 4, A) GDN_STEP2(3, B)
;         const int pos = c * 64 + t0 + dl;
;         const int tau = dir ? len - 1 - pos : pos;
;         od[(size_t)(base + tau) * 512 + h * 64 + eb * 32 + ec] = f2bf(myo);
;       }
;       __syncthreads();
;     }
;   }
;   __builtin_amdgcn_s_setprio(0);
; }
; __global__ void __launch_bounds__(NTHR, 2) mega(P p) {
;     ...
;         for (int cid = vb; cid < 256; cid += (split0 ? 256 : nvb)) gdn_chain(p, cid, smem);
	v_add_f32_dpp v228, v228, v228 quad_perm:[2,3,0,1] row_mask:0xf bank_mask:0xf bound_ctrl:1
	v_add_f32_dpp v230, v230, v230 quad_perm:[2,3,0,1] row_mask:0xf bank_mask:0xf bound_ctrl:1
	v_add_f32_dpp v232, v232, v232 quad_perm:[2,3,0,1] row_mask:0xf bank_mask:0xf bound_ctrl:1
	v_add_f32_dpp v234, v234, v234 quad_perm:[2,3,0,1] row_mask:0xf bank_mask:0xf bound_ctrl:1
	v_add_f32_dpp v236, v228, v228 row_half_mirror row_mask:0xf bank_mask:0xf bound_ctrl:1
	v_add_f32_dpp v240, v230, v230 row_half_mirror row_mask:0xf bank_mask:0xf bound_ctrl:1
	v_add_f32_dpp v238, v232, v232 row_half_mirror row_mask:0xf bank_mask:0xf bound_ctrl:1
	v_add_f32_dpp v241, v234, v234 row_half_mirror row_mask:0xf bank_mask:0xf bound_ctrl:1
	v_mul_f32_e32 v246, v44, v42
	v_fma_f32 v239, -v42, v236, v40
	v_pk_mul_f32 v[240:241], v[42:43], v[240:241] op_sel_hi:[0,1]
	v_pk_mul_f32 v[242:243], v[42:43], v[238:239]
	v_mul_f32_e32 v247, v44, v243
	v_fma_f32 v240, v60, v243, v240
	v_fma_f32 v241, v62, v243, v241
	v_fma_f32 v244, v61, v243, v242
	v_fma_f32 v240, -v44, v240, v41
	v_pk_mul_f32 v[248:249], v[8:9], v[246:247] op_sel:[0,1]
	v_pk_mul_f32 v[250:251], v[10:11], v[246:247] op_sel:[0,1]
	v_pk_mul_f32 v[240:241], v[44:45], v[240:241] op_sel:[1,0] op_sel_hi:[0,1]
	v_pk_mul_f32 v[252:253], v[12:13], v[246:247] op_sel:[0,1]
	v_pk_mul_f32 v[254:255], v[14:15], v[246:247] op_sel:[0,1]
	v_pk_fma_f32 v[0:1], v[246:247], v[0:1], v[248:249] op_sel_hi:[0,1,1]
	v_pk_fma_f32 v[2:3], v[246:247], v[2:3], v[250:251] op_sel_hi:[0,1,1]
	v_pk_fma_f32 v[4:5], v[246:247], v[4:5], v[252:253] op_sel_hi:[0,1,1]
	v_pk_fma_f32 v[6:7], v[246:247], v[6:7], v[254:255] op_sel_hi:[0,1,1]
	v_fma_f32 v245, v63, v240, v241
	v_pk_fma_f32 v[0:1], v[16:17], v[240:241], v[0:1] op_sel_hi:[1,0,1]
	v_pk_fma_f32 v[2:3], v[18:19], v[240:241], v[2:3] op_sel_hi:[1,0,1]
	v_pk_fma_f32 v[4:5], v[20:21], v[240:241], v[4:5] op_sel_hi:[1,0,1]
	v_pk_fma_f32 v[6:7], v[22:23], v[240:241], v[6:7] op_sel_hi:[1,0,1]
	v_cndmask_b32_e64 v83, v83, v244, s[86:87]
	v_cndmask_b32_e64 v83, v83, v245, s[88:89]
	s_waitcnt lgkmcnt(0)
	ds_read_b128 v[8:11], v56 offset:17920
	ds_read_b128 v[12:15], v56 offset:17936
	ds_read_b128 v[16:19], v56 offset:18176
	ds_read_b128 v[20:23], v56 offset:18192
	ds_read_b128 v[24:27], v56 offset:1536
	ds_read_b128 v[28:31], v56 offset:1552
	ds_read_b128 v[32:35], v56 offset:1792
	ds_read_b128 v[36:39], v56 offset:1808
	ds_read2_b32 v[40:41], v57 offset0:192 offset1:224
	ds_read_b128 v[42:45], v59 offset:96
	ds_read_b128 v[60:63], v59 offset:112
	v_pk_mul_f32 v[228:229], v[84:85], v[0:1]
	v_pk_mul_f32 v[230:231], v[92:93], v[0:1]
	v_pk_mul_f32 v[232:233], v[102:103], v[0:1]
	v_pk_mul_f32 v[234:235], v[120:121], v[0:1]
	v_pk_fma_f32 v[228:229], v[86:87], v[2:3], v[228:229]
	v_pk_fma_f32 v[230:231], v[94:95], v[2:3], v[230:231]
	v_pk_fma_f32 v[232:233], v[104:105], v[2:3], v[232:233]
	v_pk_fma_f32 v[234:235], v[122:123], v[2:3], v[234:235]
	v_pk_fma_f32 v[228:229], v[88:89], v[4:5], v[228:229]
	v_pk_fma_f32 v[230:231], v[98:99], v[4:5], v[230:231]
	v_pk_fma_f32 v[232:233], v[106:107], v[4:5], v[232:233]
	v_pk_fma_f32 v[234:235], v[124:125], v[4:5], v[234:235]
	v_pk_fma_f32 v[228:229], v[90:91], v[6:7], v[228:229]
	v_pk_fma_f32 v[230:231], v[100:101], v[6:7], v[230:231]
	v_pk_fma_f32 v[232:233], v[108:109], v[6:7], v[232:233]
	v_pk_fma_f32 v[234:235], v[126:127], v[6:7], v[234:235]
	v_add_f32_e32 v228, v228, v229
	v_add_f32_e32 v230, v230, v231
	v_add_f32_e32 v232, v232, v233
	v_add_f32_e32 v234, v234, v235
	v_add_f32_dpp v228, v228, v228 quad_perm:[1,0,3,2] row_mask:0xf bank_mask:0xf bound_ctrl:1
	v_add_f32_dpp v230, v230, v230 quad_perm:[1,0,3,2] row_mask:0xf bank_mask:0xf bound_ctrl:1
	v_add_f32_dpp v232, v232, v232 quad_perm:[1,0,3,2] row_mask:0xf bank_mask:0xf bound_ctrl:1
	v_add_f32_dpp v234, v234, v234 quad_perm:[1,0,3,2] row_mask:0xf bank_mask:0xf bound_ctrl:1
	v_add_f32_dpp v228, v228, v228 quad_perm:[2,3,0,1] row_mask:0xf bank_mask:0xf bound_ctrl:1
	v_add_f32_dpp v230, v230, v230 quad_perm:[2,3,0,1] row_mask:0xf bank_mask:0xf bound_ctrl:1
	v_add_f32_dpp v232, v232, v232 quad_perm:[2,3,0,1] row_mask:0xf bank_mask:0xf bound_ctrl:1
	v_add_f32_dpp v234, v234, v234 quad_perm:[2,3,0,1] row_mask:0xf bank_mask:0xf bound_ctrl:1
	v_add_f32_dpp v236, v228, v228 row_half_mirror row_mask:0xf bank_mask:0xf bound_ctrl:1
	v_add_f32_dpp v240, v230, v230 row_half_mirror row_mask:0xf bank_mask:0xf bound_ctrl:1
	v_add_f32_dpp v238, v232, v232 row_half_mirror row_mask:0xf bank_mask:0xf bound_ctrl:1
	v_add_f32_dpp v241, v234, v234 row_half_mirror row_mask:0xf bank_mask:0xf bound_ctrl:1
	v_mul_f32_e32 v246, v66, v64
	v_fma_f32 v239, -v64, v236, v128
	v_pk_mul_f32 v[240:241], v[64:65], v[240:241] op_sel_hi:[0,1]
	v_pk_mul_f32 v[242:243], v[64:65], v[238:239]
	v_mul_f32_e32 v247, v66, v243
	v_fma_f32 v240, v224, v243, v240
	v_fma_f32 v241, v226, v243, v241
	v_fma_f32 v244, v225, v243, v242
	v_fma_f32 v240, -v66, v240, v129
	v_pk_mul_f32 v[248:249], v[84:85], v[246:247] op_sel:[0,1]
	v_pk_mul_f32 v[250:251], v[86:87], v[246:247] op_sel:[0,1]
	v_pk_mul_f32 v[240:241], v[66:67], v[240:241] op_sel:[1,0] op_sel_hi:[0,1]
	v_pk_mul_f32 v[252:253], v[88:89], v[246:247] op_sel:[0,1]
	v_pk_mul_f32 v[254:255], v[90:91], v[246:247] op_sel:[0,1]
	v_pk_fma_f32 v[0:1], v[246:247], v[0:1], v[248:249] op_sel_hi:[0,1,1]
	v_pk_fma_f32 v[2:3], v[246:247], v[2:3], v[250:251] op_sel_hi:[0,1,1]
	v_pk_fma_f32 v[4:5], v[246:247], v[4:5], v[252:253] op_sel_hi:[0,1,1]
	v_pk_fma_f32 v[6:7], v[246:247], v[6:7], v[254:255] op_sel_hi:[0,1,1]
	v_fma_f32 v245, v227, v240, v241
	v_pk_fma_f32 v[0:1], v[92:93], v[240:241], v[0:1] op_sel_hi:[1,0,1]
	v_pk_fma_f32 v[2:3], v[94:95], v[240:241], v[2:3] op_sel_hi:[1,0,1]
	v_pk_fma_f32 v[4:5], v[98:99], v[240:241], v[4:5] op_sel_hi:[1,0,1]
	v_pk_fma_f32 v[6:7], v[100:101], v[240:241], v[6:7] op_sel_hi:[1,0,1]
	v_cndmask_b32_e64 v83, v83, v244, s[90:91]
	v_cndmask_b32_e64 v83, v83, v245, s[92:93]
	s_add_i32 s0, s0, 8
	v_add_u32_e32 v130, s0, v82
	v_cndmask_b32_e64 v130, v58, v130, s[74:75]
	v_add_u32_e32 v130, s49, v130
	v_ashrrev_i32_e32 v131, 31, v130
	s_addk_i32 s1, 0x80
	v_lshlrev_b64 v[130:131], 10, v[130:131]
	v_cvt_pk_bf16_f32 v83, v83, s0
	v_add_u32_e32 v57, 0x400, v57
	v_add_u32_e32 v56, 0x800, v56
	s_cmp_gt_u32 s0, 55
	v_add_u32_e32 v58, -8, v58
	v_lshl_add_u64 v[130:131], v[52:53], 0, v[130:131]
	global_store_short v[130:131], v83, off
	s_cbranch_scc0 .Lgdn_rec
	s_add_i32 s54, s54, 1
	v_add_u32_e32 v82, 64, v82
	s_cmp_eq_u32 s54, s52
	v_subrev_u32_e32 v81, 64, v81
	s_waitcnt lgkmcnt(0)
	s_barrier
	s_cbranch_scc0 .LBB0_948
	s_mov_b64 s[0:1], 0
	s_and_b64 vcc, exec, s[42:43]
	s_cbranch_vccz .LBB0_947
	s_setprio 0
	v_readlane_b32 s0, v221, 38
	s_add_i32 s44, s44, s0
	v_readlane_b32 s92, v218, 45
	s_cmpk_lt_i32 s44, 0x100
	v_readlane_b32 s54, v218, 44
	v_readlane_b32 s93, v218, 46
	s_movk_i32 s48, 0x47ff
	s_movk_i32 s49, 0x600
	s_cbranch_scc1 .LBB0_930
